# mix_b hgrn_out: loop-invariant norm gain loads hoisted to one batch per chunk after the last MFMA; per-block reload waits (which also drained the output stores) removed; loop latch waits only for load
# speedup vs baseline: 1.0172x; 1.0053x over previous
.LBB0_1242:
	s_or_b64 exec, exec, s[0:1]
	s_add_i32 s15, s15, 16
	s_add_i32 s14, s14, 64
	s_add_i32 s16, s16, 1
	v_mov_b64_e32 v[94:95], v[18:19]
	v_mov_b64_e32 v[82:83], v[26:27]
	v_mov_b64_e32 v[70:71], v[42:43]
	s_waitcnt vmcnt(4)
	v_mov_b64_e32 v[58:59], v[50:51]
	v_mov_b64_e32 v[90:91], v[10:11]
	v_mov_b64_e32 v[78:79], v[22:23]
	v_mov_b64_e32 v[66:67], v[34:35]
	s_waitcnt vmcnt(4)
	v_mov_b64_e32 v[54:55], v[46:47]
	v_mov_b64_e32 v[98:99], v[14:15]
	v_mov_b64_e32 v[86:87], v[6:7]
	v_mov_b64_e32 v[74:75], v[38:39]
	v_mov_b64_e32 v[62:63], v[30:31]
	s_cmpk_lg_i32 s14, 0x100
	v_mov_b64_e32 v[92:93], v[16:17]
	v_mov_b64_e32 v[80:81], v[24:25]
	v_mov_b64_e32 v[68:69], v[40:41]
	v_mov_b64_e32 v[56:57], v[48:49]
	v_mov_b64_e32 v[88:89], v[8:9]
	v_mov_b64_e32 v[76:77], v[20:21]
	v_mov_b64_e32 v[64:65], v[32:33]
	v_mov_b64_e32 v[52:53], v[44:45]
	v_mov_b64_e32 v[96:97], v[12:13]
	v_mov_b64_e32 v[84:85], v[4:5]
	v_mov_b64_e32 v[72:73], v[36:37]
	v_mov_b64_e32 v[60:61], v[28:29]
	s_cbranch_scc0 .LBB0_1219

.LBB0_1260:
	s_barrier
	ds_read_b128 v[100:103], v0 offset:27648
	ds_read_b128 v[104:107], v0 offset:29952
	s_waitcnt vmcnt(9) lgkmcnt(1)
	v_mfma_f32_16x16x32_bf16 v[108:111], v[92:95], v[100:103], v[108:111]
	v_lshlrev_b32_e32 v145, 3, v2
	v_and_b32_e32 v2, 64, v229
	v_add_u32_e32 v2, 64, v2
	s_waitcnt lgkmcnt(0)
	v_mfma_f32_16x16x32_bf16 v[92:95], v[92:95], v[104:107], v[112:115]
	s_waitcnt vmcnt(7)
	v_mfma_f32_16x16x32_bf16 v[112:115], v[96:99], v[100:103], v[116:119]
	v_mfma_f32_16x16x32_bf16 v[116:119], v[96:99], v[104:107], v[120:123]
	v_mfma_f32_16x16x32_bf16 v[120:123], v[88:91], v[100:103], v[124:127]
	v_mfma_f32_16x16x32_bf16 v[124:127], v[88:91], v[104:107], v[128:131]
	v_mfma_f32_16x16x32_bf16 v[128:131], v[84:87], v[100:103], v[132:135]
	v_mfma_f32_16x16x32_bf16 v[104:107], v[84:87], v[104:107], v[136:139]
	s_nop 1
	ds_read_b128 v[132:135], v0 offset:27712
	ds_read_b128 v[136:139], v0 offset:30016
	v_xor_b32_e32 v0, 16, v229
	v_cmp_lt_i32_e32 vcc, v0, v2
	s_waitcnt lgkmcnt(1)
	v_mfma_f32_16x16x32_bf16 v[100:103], v[68:71], v[132:135], v[108:111]
	v_cndmask_b32_e32 v0, v229, v0, vcc
	s_waitcnt lgkmcnt(0)
	v_mfma_f32_16x16x32_bf16 v[88:91], v[68:71], v[136:139], v[92:95]
	s_waitcnt vmcnt(6)
	v_mfma_f32_16x16x32_bf16 v[96:99], v[72:75], v[132:135], v[112:115]
	v_mfma_f32_16x16x32_bf16 v[84:87], v[72:75], v[136:139], v[116:119]
	s_waitcnt vmcnt(5)
	v_mfma_f32_16x16x32_bf16 v[92:95], v[80:83], v[132:135], v[120:123]
	s_nop 4
	v_mul_f32_e32 v3, v99, v99
	v_fmac_f32_e32 v3, v98, v98
	v_mfma_f32_16x16x32_bf16 v[72:75], v[80:83], v[136:139], v[124:127]
	s_waitcnt vmcnt(4)
	v_mfma_f32_16x16x32_bf16 v[80:83], v[76:79], v[132:135], v[128:131]
	v_mfma_f32_16x16x32_bf16 v[68:71], v[76:79], v[136:139], v[104:107]
	v_lshlrev_b32_e32 v244, 2, v145
	global_load_dwordx4 v[112:115], v244, s[4:5]
	global_load_dwordx4 v[116:119], v244, s[4:5] offset:16
	global_load_dwordx4 v[120:123], v244, s[4:5] offset:128
	global_load_dwordx4 v[124:127], v244, s[4:5] offset:144
	v_lshlrev_b32_e32 v77, 2, v0
	v_xor_b32_e32 v0, 32, v229
	v_cmp_lt_i32_e32 vcc, v0, v2
	v_mul_f32_e32 v2, v103, v103
	v_fmac_f32_e32 v2, v102, v102
	v_cndmask_b32_e32 v0, v229, v0, vcc
	v_lshlrev_b32_e32 v78, 2, v0
	v_mul_f32_e32 v0, v101, v101
	v_fmac_f32_e32 v0, v100, v100
	v_add_f32_e32 v0, v0, v2
	v_mul_f32_e32 v2, v97, v97
	v_fmac_f32_e32 v2, v96, v96
	v_add_f32_e32 v2, v2, v3
	v_add_f32_e32 v0, v0, v2
	v_mul_f32_e32 v2, v93, v93
	v_mul_f32_e32 v3, v95, v95
	v_fmac_f32_e32 v2, v92, v92
	v_fmac_f32_e32 v3, v94, v94
	v_add_f32_e32 v2, v2, v3
	v_add_f32_e32 v0, v0, v2
	v_mul_f32_e32 v2, v81, v81
	v_mul_f32_e32 v3, v83, v83
	v_fmac_f32_e32 v2, v80, v80
	v_fmac_f32_e32 v3, v82, v82
	v_add_f32_e32 v2, v2, v3
	v_add_f32_e32 v0, v0, v2
	ds_bpermute_b32 v2, v77, v0
	v_cmp_gt_u32_e32 vcc, s17, v144
	v_lshlrev_b32_e32 v76, 2, v145
	s_waitcnt lgkmcnt(0)
	v_add_f32_e32 v2, v0, v2
	ds_bpermute_b32 v3, v78, v2
	v_lshlrev_b32_e32 v0, 1, v145
	s_waitcnt vmcnt(0)
	s_and_saveexec_b64 s[0:1], vcc
	s_cbranch_execz .LBB0_1262
	s_waitcnt lgkmcnt(0)
	v_add_f32_e32 v2, v2, v3
	v_fmamk_f32 v2, v2, 0x3c800000, v226
	v_cmp_gt_f32_e32 vcc, s86, v2
	v_mul_f32_e32 v3, 0x4b800000, v2
	s_nop 0
	v_cndmask_b32_e32 v2, v2, v3, vcc
	v_rsq_f32_e32 v2, v2
	s_nop 0
	v_mul_f32_e32 v3, 0x45800000, v2
	v_cndmask_b32_e32 v79, v2, v3, vcc
	v_mul_f32_e32 v100, v100, v79
	v_mul_f32_e32 v101, v101, v79
	v_mul_f32_e32 v96, v96, v79
	v_mul_f32_e32 v97, v97, v79
	v_add_u32_e32 v2, s18, v144
	v_ashrrev_i32_e32 v3, 31, v2
	v_lshlrev_b64 v[2:3], 11, v[2:3]
	v_lshl_add_u64 v[2:3], s[58:59], 0, v[2:3]
	v_lshl_add_u64 v[2:3], s[6:7], 1, v[2:3]
	v_mul_f32_e32 v92, v92, v79
	v_mul_f32_e32 v93, v93, v79
	v_mul_f32_e32 v80, v80, v79
	v_mul_f32_e32 v96, v96, v116
	v_mul_f32_e32 v100, v100, v112
	v_lshlrev_b32_e32 v108, 16, v64
	v_mul_f32_e32 v101, v101, v113
	v_and_b32_e32 v64, 0xffff0000, v64
	v_mul_f32_e32 v100, v100, v108
	v_mul_f32_e32 v64, v101, v64
	v_cvt_pk_bf16_f32 v64, v100, v64
	v_mul_f32_e32 v100, v102, v79
	v_mul_f32_e32 v100, v100, v114
	v_lshlrev_b32_e32 v101, 16, v65
	v_mul_f32_e32 v100, v100, v101
	v_mul_f32_e32 v101, v103, v79
	v_mul_f32_e32 v101, v101, v115
	v_and_b32_e32 v65, 0xffff0000, v65
	v_mul_f32_e32 v65, v101, v65
	v_cvt_pk_bf16_f32 v65, v100, v65
	v_lshlrev_b32_e32 v100, 16, v66
	v_mul_f32_e32 v97, v97, v117
	v_and_b32_e32 v66, 0xffff0000, v66
	v_mul_f32_e32 v96, v96, v100
	v_mul_f32_e32 v66, v97, v66
	v_cvt_pk_bf16_f32 v66, v96, v66
	v_mul_f32_e32 v96, v98, v79
	v_mul_f32_e32 v96, v96, v118
	v_lshlrev_b32_e32 v97, 16, v67
	v_mul_f32_e32 v96, v96, v97
	v_mul_f32_e32 v97, v99, v79
	v_mul_f32_e32 v97, v97, v119
	v_and_b32_e32 v67, 0xffff0000, v67
	v_mul_f32_e32 v67, v97, v67
	v_cvt_pk_bf16_f32 v67, v96, v67
	v_lshl_add_u64 v[96:97], v[2:3], 0, v[0:1]
	v_lshl_add_u64 v[2:3], v[96:97], 0, s[76:77]
	v_add_co_u32_e32 v96, vcc, s30, v96
	s_nop 1
	v_addc_co_u32_e32 v97, vcc, 0, v97, vcc
	global_store_dwordx4 v[96:97], v[64:67], off offset:512
	s_nop 1
	s_nop 0
	v_mul_f32_e32 v64, v80, v124
	v_mul_f32_e32 v92, v92, v120
	v_lshlrev_b32_e32 v96, 16, v60
	v_mul_f32_e32 v93, v93, v121
	v_and_b32_e32 v60, 0xffff0000, v60
	v_mul_f32_e32 v92, v92, v96
	v_mul_f32_e32 v60, v93, v60
	v_cvt_pk_bf16_f32 v60, v92, v60
	v_mul_f32_e32 v92, v94, v79
	v_mul_f32_e32 v92, v92, v122
	v_lshlrev_b32_e32 v93, 16, v61
	v_lshlrev_b32_e32 v80, 16, v62
	v_mul_f32_e32 v92, v92, v93
	v_mul_f32_e32 v93, v95, v79
	v_mul_f32_e32 v64, v64, v80
	v_mul_f32_e32 v80, v81, v79
	v_mul_f32_e32 v93, v93, v123
	v_and_b32_e32 v61, 0xffff0000, v61
	v_mul_f32_e32 v65, v80, v125
	v_and_b32_e32 v62, 0xffff0000, v62
	v_mul_f32_e32 v61, v93, v61
	v_mul_f32_e32 v62, v65, v62
	v_cvt_pk_bf16_f32 v61, v92, v61
	v_cvt_pk_bf16_f32 v62, v64, v62
	v_mul_f32_e32 v64, v82, v79
	v_mul_f32_e32 v64, v64, v126
	v_lshlrev_b32_e32 v65, 16, v63
	v_mul_f32_e32 v64, v64, v65
	v_mul_f32_e32 v65, v83, v79
	v_mul_f32_e32 v65, v65, v127
	v_and_b32_e32 v63, 0xffff0000, v63
	v_mul_f32_e32 v63, v65, v63
	v_cvt_pk_bf16_f32 v63, v64, v63
	global_store_dwordx4 v[2:3], v[60:63], off offset:64
.LBB0_1262:
	s_or_b64 exec, exec, s[0:1]
	v_mul_f32_e32 v2, v89, v89
	s_waitcnt lgkmcnt(0)
	v_mul_f32_e32 v3, v91, v91
	v_fmac_f32_e32 v2, v88, v88
	v_fmac_f32_e32 v3, v90, v90
	v_add_f32_e32 v2, v2, v3
	v_mul_f32_e32 v3, v85, v85
	s_waitcnt vmcnt(2)
	v_mul_f32_e32 v60, v87, v87
	v_fmac_f32_e32 v3, v84, v84
	v_fmac_f32_e32 v60, v86, v86
	v_add_f32_e32 v3, v3, v60
	v_add_f32_e32 v2, v2, v3
	v_mul_f32_e32 v3, v73, v73
	v_mul_f32_e32 v60, v75, v75
	v_fmac_f32_e32 v3, v72, v72
	v_fmac_f32_e32 v60, v74, v74
	v_add_f32_e32 v3, v3, v60
	v_add_f32_e32 v2, v2, v3
	v_mul_f32_e32 v3, v69, v69
	v_mul_f32_e32 v60, v71, v71
	v_fmac_f32_e32 v3, v68, v68
	v_fmac_f32_e32 v60, v70, v70
	v_add_f32_e32 v3, v3, v60
	v_add_f32_e32 v2, v2, v3
	ds_bpermute_b32 v3, v77, v2
	v_cmp_gt_u32_e32 vcc, s17, v143
	s_waitcnt lgkmcnt(0)
	v_add_f32_e32 v2, v2, v3
	ds_bpermute_b32 v3, v78, v2
	s_and_saveexec_b64 s[0:1], vcc
	s_cbranch_execz .LBB0_1242
	s_waitcnt lgkmcnt(0)
	v_add_f32_e32 v2, v2, v3
	v_fmamk_f32 v2, v2, 0x3c800000, v226
	v_cmp_gt_f32_e32 vcc, s86, v2
	v_mul_f32_e32 v3, 0x4b800000, v2
	s_waitcnt vmcnt(3)
	v_lshlrev_b32_e32 v66, 16, v56
	v_cndmask_b32_e32 v2, v2, v3, vcc
	v_rsq_f32_e32 v2, v2
	v_and_b32_e32 v56, 0xffff0000, v56
	v_mul_f32_e32 v3, 0x45800000, v2
	v_cndmask_b32_e32 v60, v2, v3, vcc
	v_mul_f32_e32 v61, v88, v60
	v_add_u32_e32 v2, s18, v143
	v_ashrrev_i32_e32 v3, 31, v2
	v_lshlrev_b64 v[2:3], 11, v[2:3]
	v_lshl_add_u64 v[2:3], s[58:59], 0, v[2:3]
	v_lshl_add_u64 v[2:3], s[6:7], 1, v[2:3]
	v_mul_f32_e32 v61, v61, v112
	v_mul_f32_e32 v61, v61, v66
	v_mul_f32_e32 v66, v89, v60
	v_mul_f32_e32 v66, v66, v113
	v_mul_f32_e32 v56, v66, v56
	v_cvt_pk_bf16_f32 v56, v61, v56
	v_mul_f32_e32 v61, v90, v60
	v_mul_f32_e32 v61, v61, v114
	v_lshlrev_b32_e32 v66, 16, v57
	v_mul_f32_e32 v61, v61, v66
	v_mul_f32_e32 v66, v91, v60
	v_mul_f32_e32 v66, v66, v115
	v_and_b32_e32 v57, 0xffff0000, v57
	v_mul_f32_e32 v57, v66, v57
	v_cvt_pk_bf16_f32 v57, v61, v57
	v_mul_f32_e32 v61, v84, v60
	v_mul_f32_e32 v61, v61, v116
	v_lshlrev_b32_e32 v62, 16, v58
	v_mul_f32_e32 v61, v61, v62
	v_mul_f32_e32 v62, v85, v60
	v_mul_f32_e32 v62, v62, v117
	v_and_b32_e32 v58, 0xffff0000, v58
	v_mul_f32_e32 v58, v62, v58
	v_cvt_pk_bf16_f32 v58, v61, v58
	v_mul_f32_e32 v61, v86, v60
	v_mul_f32_e32 v61, v61, v118
	v_lshlrev_b32_e32 v62, 16, v59
	v_mul_f32_e32 v61, v61, v62
	v_mul_f32_e32 v62, v87, v60
	v_mul_f32_e32 v62, v62, v119
	v_and_b32_e32 v59, 0xffff0000, v59
	v_mul_f32_e32 v59, v62, v59
	v_lshl_add_u64 v[62:63], v[2:3], 0, v[0:1]
	v_lshl_add_u64 v[2:3], v[62:63], 0, s[76:77]
	v_add_co_u32_e32 v62, vcc, s30, v62
	v_cvt_pk_bf16_f32 v59, v61, v59
	v_mul_f32_e32 v0, v72, v60
	s_nop 0
	v_addc_co_u32_e32 v63, vcc, 0, v63, vcc
	global_store_dwordx4 v[62:63], v[56:59], off offset:512
	s_nop 1
	s_nop 0
	v_lshlrev_b32_e32 v61, 16, v52
	v_and_b32_e32 v52, 0xffff0000, v52
	v_mul_f32_e32 v0, v0, v120
	v_mul_f32_e32 v0, v0, v61
	v_mul_f32_e32 v61, v73, v60
	v_mul_f32_e32 v61, v61, v121
	v_mul_f32_e32 v52, v61, v52
	v_cvt_pk_bf16_f32 v52, v0, v52
	v_mul_f32_e32 v0, v74, v60
	v_mul_f32_e32 v0, v0, v122
	v_lshlrev_b32_e32 v61, 16, v53
	v_mul_f32_e32 v0, v0, v61
	v_mul_f32_e32 v61, v75, v60
	v_mul_f32_e32 v61, v61, v123
	v_and_b32_e32 v53, 0xffff0000, v53
	v_mul_f32_e32 v53, v61, v53
	v_cvt_pk_bf16_f32 v53, v0, v53
	v_mul_f32_e32 v0, v68, v60
	v_mul_f32_e32 v0, v0, v124
	v_lshlrev_b32_e32 v56, 16, v54
	v_mul_f32_e32 v0, v0, v56
	v_mul_f32_e32 v56, v69, v60
	v_mul_f32_e32 v56, v56, v125
	v_and_b32_e32 v54, 0xffff0000, v54
	v_mul_f32_e32 v54, v56, v54
	v_cvt_pk_bf16_f32 v54, v0, v54
	v_mul_f32_e32 v0, v70, v60
	v_mul_f32_e32 v0, v0, v126
	v_lshlrev_b32_e32 v56, 16, v55
	v_mul_f32_e32 v0, v0, v56
	v_mul_f32_e32 v56, v71, v60
	v_mul_f32_e32 v56, v56, v127
	v_and_b32_e32 v55, 0xffff0000, v55
	v_mul_f32_e32 v55, v56, v55
	v_cvt_pk_bf16_f32 v55, v0, v55
	global_store_dwordx4 v[2:3], v[52:55], off offset:64
	s_branch .LBB0_1242
